# out-proj epilogue: X1B stores widened to dwordx4 (column-block pairs exchanged between lane pairs with v_permlane16_swap), 16 stores per unit instead of 32
# speedup vs baseline: 1.0305x; 1.0028x over previous
; DI u32x2 pk4(f32x4 v) { u32x2 r; r.x = pk2(v[0], v[1]); r.y = pk2(v[2], v[3]); return r; }
;     DI void operator()(const AccT& acc, const Unit& u, int wr, int wc, int fr, int fq, LAS unsigned char*) const {
;         const int col0 = u.pn * 256 + wc * 32 + 4 * fq;
; #pragma unroll
;         for (int ai = 0; ai < 2; ++ai)
; #pragma unroll
;             for (int m = 0; m < 4; ++m) {
;                 const int row = u.pm * 256 + ai * 128 + wr * 64 + m * 16 + fr;
;                 const float* xr = (row < SEQ ? xp + (size_t)row * DM : xs + (size_t)(row - SEQ) * DM) + col0;
;                 bf16_t* brow = X1B + (size_t)(row < SEQ ? row + 2 : row + (X1B_PROMPT_ROWS - SEQ)) * DM + col0;
;                 float ss = 0.f;
; #pragma unroll
;                 for (int bj = 0; bj < 2; ++bj)
; #pragma unroll
;                     for (int n = 0; n < 2; ++n) {
;                         const int c = bj * 128 + n * 16;
;                         const f32x4 o = *(const f32x4*)(xr + c) + acc[ai][bj][m][n];
;                         *(u32x2*)(brow + c) = pk4(o);
;                         ss += (o[0] * o[0] + o[1] * o[1]) + (o[2] * o[2] + o[3] * o[3]);
;                     }
;                 ss += __shfl_xor(ss, 16); ss += __shfl_xor(ss, 32);
.LBB0_960:
	v_lshl_add_u32 v130, s31, 8, v132
	v_lshl_or_b32 v128, s33, 8, v134
	s_cmp_lt_i32 s31, 64
	s_cselect_b32 s16, s44, s46
	s_cselect_b32 s17, s45, s47
	s_cselect_b32 s42, 0, 0x4000000
	s_cselect_b32 s43, 1, 64
	s_lshl_b32 s43, s43, 12
	s_sub_u32 s16, s16, s42
	s_subb_u32 s17, s17, 0
	s_add_u32 s18, s56, s43
	s_addc_u32 s19, s57, 0
	v_lshlrev_b32_e32 v129, 12, v130
	v_lshlrev_b32_e32 v131, 11, v130
	v_lshl_add_u32 v129, v128, 2, v129
	v_lshl_add_u32 v131, v128, 1, v131
	v_lshlrev_b32_e32 v130, 2, v130
	v_and_b32_e32 v128, 16, v226
	v_lshrrev_b32_e32 v144, 1, v128
	v_add3_u32 v131, v131, v128, v144
	global_load_dwordx4 v[146:149], v129, s[16:17]
	global_load_dwordx4 v[150:153], v129, s[16:17] offset:64
	global_load_dwordx4 v[154:157], v129, s[16:17] offset:512
	global_load_dwordx4 v[158:161], v129, s[16:17] offset:576
	s_add_u32 s36, s16, 0x10000
	s_addc_u32 s37, s17, 0
	global_load_dwordx4 v[182:185], v129, s[36:37]
	global_load_dwordx4 v[186:189], v129, s[36:37] offset:64
	global_load_dwordx4 v[190:193], v129, s[36:37] offset:512
	global_load_dwordx4 v[194:197], v129, s[36:37] offset:576
	s_add_u32 s36, s16, 0x20000
	s_addc_u32 s37, s17, 0
	global_load_dwordx4 v[198:201], v129, s[36:37]
	global_load_dwordx4 v[202:205], v129, s[36:37] offset:64
	global_load_dwordx4 v[206:209], v129, s[36:37] offset:512
	global_load_dwordx4 v[210:213], v129, s[36:37] offset:576
	s_add_u32 s36, s16, 0x30000
	s_addc_u32 s37, s17, 0
	global_load_dwordx4 v[162:165], v129, s[36:37]
	global_load_dwordx4 v[214:217], v129, s[36:37] offset:64
	global_load_dwordx4 v[136:139], v129, s[36:37] offset:512
	global_load_dwordx4 v[140:143], v129, s[36:37] offset:576
	s_waitcnt vmcnt(12)
	v_pk_add_f32 v[146:147], v[124:125], v[146:147]
	v_pk_add_f32 v[148:149], v[126:127], v[148:149]
	v_pk_add_f32 v[150:151], v[120:121], v[150:151]
	v_pk_add_f32 v[152:153], v[122:123], v[152:153]
	v_pk_add_f32 v[154:155], v[116:117], v[154:155]
	v_pk_add_f32 v[156:157], v[118:119], v[156:157]
	v_pk_add_f32 v[158:159], v[112:113], v[158:159]
	v_pk_add_f32 v[160:161], v[114:115], v[160:161]
	s_add_u32 s36, s16, 0x80000
	s_addc_u32 s37, s17, 0
	global_load_dwordx4 v[124:127], v129, s[36:37]
	global_load_dwordx4 v[120:123], v129, s[36:37] offset:64
	global_load_dwordx4 v[116:119], v129, s[36:37] offset:512
	global_load_dwordx4 v[112:115], v129, s[36:37] offset:576
	s_waitcnt vmcnt(12)
	v_pk_add_f32 v[182:183], v[108:109], v[182:183]
	v_pk_add_f32 v[184:185], v[110:111], v[184:185]
	v_pk_add_f32 v[186:187], v[104:105], v[186:187]
	v_pk_add_f32 v[188:189], v[106:107], v[188:189]
	v_pk_add_f32 v[190:191], v[100:101], v[190:191]
	v_pk_add_f32 v[192:193], v[102:103], v[192:193]
	v_pk_add_f32 v[194:195], v[96:97], v[194:195]
	v_pk_add_f32 v[196:197], v[98:99], v[196:197]
	s_add_u32 s36, s16, 0x90000
	s_addc_u32 s37, s17, 0
	global_load_dwordx4 v[108:111], v129, s[36:37]
	global_load_dwordx4 v[104:107], v129, s[36:37] offset:64
	global_load_dwordx4 v[100:103], v129, s[36:37] offset:512
	global_load_dwordx4 v[96:99], v129, s[36:37] offset:576
	s_waitcnt vmcnt(12)
	v_pk_add_f32 v[198:199], v[92:93], v[198:199]
	v_pk_add_f32 v[200:201], v[94:95], v[200:201]
	v_pk_add_f32 v[202:203], v[88:89], v[202:203]
	v_pk_add_f32 v[204:205], v[90:91], v[204:205]
	v_pk_add_f32 v[206:207], v[84:85], v[206:207]
	v_pk_add_f32 v[208:209], v[86:87], v[208:209]
	v_pk_add_f32 v[210:211], v[80:81], v[210:211]
	v_pk_add_f32 v[212:213], v[82:83], v[212:213]
	s_add_u32 s36, s16, 0xa0000
	s_addc_u32 s37, s17, 0
	global_load_dwordx4 v[92:95], v129, s[36:37]
	global_load_dwordx4 v[88:91], v129, s[36:37] offset:64
	global_load_dwordx4 v[84:87], v129, s[36:37] offset:512
	global_load_dwordx4 v[80:83], v129, s[36:37] offset:576
	s_waitcnt vmcnt(12)
	v_pk_add_f32 v[162:163], v[76:77], v[162:163]
	v_pk_add_f32 v[164:165], v[78:79], v[164:165]
	v_pk_add_f32 v[214:215], v[72:73], v[214:215]
	v_pk_add_f32 v[216:217], v[74:75], v[216:217]
	v_pk_add_f32 v[136:137], v[68:69], v[136:137]
	v_pk_add_f32 v[138:139], v[70:71], v[138:139]
	v_pk_add_f32 v[140:141], v[64:65], v[140:141]
	v_pk_add_f32 v[142:143], v[66:67], v[142:143]
	s_add_u32 s36, s16, 0xb0000
	s_addc_u32 s37, s17, 0
	global_load_dwordx4 v[76:79], v129, s[36:37]
	global_load_dwordx4 v[72:75], v129, s[36:37] offset:64
	global_load_dwordx4 v[68:71], v129, s[36:37] offset:512
	global_load_dwordx4 v[64:67], v129, s[36:37] offset:576
	v_pk_mul_f32 v[166:167], v[146:147], v[146:147]
	v_pk_mul_f32 v[144:145], v[148:149], v[148:149]
	v_pk_fma_f32 v[166:167], v[150:151], v[150:151], v[166:167]
	v_pk_fma_f32 v[144:145], v[152:153], v[152:153], v[144:145]
	v_pk_fma_f32 v[166:167], v[154:155], v[154:155], v[166:167]
	v_pk_fma_f32 v[144:145], v[156:157], v[156:157], v[144:145]
	v_pk_fma_f32 v[166:167], v[158:159], v[158:159], v[166:167]
	v_pk_fma_f32 v[144:145], v[160:161], v[160:161], v[144:145]
	s_nop 0
	v_pk_add_f32 v[166:167], v[166:167], v[144:145]
	v_cvt_pk_bf16_f32 v146, v146, v147
	v_cvt_pk_bf16_f32 v147, v148, v149
	v_cvt_pk_bf16_f32 v148, v150, v151
	v_cvt_pk_bf16_f32 v149, v152, v153
	v_cvt_pk_bf16_f32 v154, v154, v155
	v_cvt_pk_bf16_f32 v155, v156, v157
	v_cvt_pk_bf16_f32 v156, v158, v159
	v_cvt_pk_bf16_f32 v157, v160, v161
	v_add_f32_e32 v218, v166, v167
	s_nop 0
	v_permlane16_swap_b32_e32 v146, v148
	v_permlane16_swap_b32_e32 v147, v149
	v_permlane16_swap_b32_e32 v154, v156
	v_permlane16_swap_b32_e32 v155, v157
	global_store_dwordx4 v131, v[146:149], s[18:19]
	global_store_dwordx4 v131, v[154:157], s[18:19] offset:256
	v_mov_b32_e32 v219, v218
	s_nop 1
	v_permlane16_swap_b32_e32 v219, v218
	v_add_f32_e32 v218, v218, v219
	v_mov_b32_e32 v219, v218
	s_nop 1
; DI u32x2 pk4(f32x4 v) { u32x2 r; r.x = pk2(v[0], v[1]); r.y = pk2(v[2], v[3]); return r; }
;     DI void operator()(const AccT& acc, const Unit& u, int wr, int wc, int fr, int fq, LAS unsigned char*) const {
;         const int col0 = u.pn * 256 + wc * 32 + 4 * fq;
; #pragma unroll
;         for (int ai = 0; ai < 2; ++ai)
; #pragma unroll
;             for (int m = 0; m < 4; ++m) {
;                 const int row = u.pm * 256 + ai * 128 + wr * 64 + m * 16 + fr;
;                 const float* xr = (row < SEQ ? xp + (size_t)row * DM : xs + (size_t)(row - SEQ) * DM) + col0;
;                 bf16_t* brow = X1B + (size_t)(row < SEQ ? row + 2 : row + (X1B_PROMPT_ROWS - SEQ)) * DM + col0;
;                 float ss = 0.f;
; #pragma unroll
;                 for (int bj = 0; bj < 2; ++bj)
; #pragma unroll
;                     for (int n = 0; n < 2; ++n) {
;                         const int c = bj * 128 + n * 16;
;                         const f32x4 o = *(const f32x4*)(xr + c) + acc[ai][bj][m][n];
;                         *(u32x2*)(brow + c) = pk4(o);
;                         ss += (o[0] * o[0] + o[1] * o[1]) + (o[2] * o[2] + o[3] * o[3]);
;                     }
;                 ss += __shfl_xor(ss, 16); ss += __shfl_xor(ss, 32);
;                 if (fq == 0) unsafeAtomicAdd(sumsq + row, ss);
;             }
	v_permlane32_swap_b32_e32 v219, v218
	v_add_f32_e32 v218, v218, v219
	s_and_saveexec_b64 s[0:1], s[40:41]
	global_atomic_add_f32 v130, v218, s[58:59]
	s_mov_b64 exec, s[0:1]
	v_pk_mul_f32 v[166:167], v[182:183], v[182:183]
	v_pk_mul_f32 v[144:145], v[184:185], v[184:185]
	v_pk_fma_f32 v[166:167], v[186:187], v[186:187], v[166:167]
	v_pk_fma_f32 v[144:145], v[188:189], v[188:189], v[144:145]
	v_pk_fma_f32 v[166:167], v[190:191], v[190:191], v[166:167]
	v_pk_fma_f32 v[144:145], v[192:193], v[192:193], v[144:145]
	v_pk_fma_f32 v[166:167], v[194:195], v[194:195], v[166:167]
	v_pk_fma_f32 v[144:145], v[196:197], v[196:197], v[144:145]
	s_nop 0
	v_pk_add_f32 v[166:167], v[166:167], v[144:145]
	s_add_u32 s48, s18, 0x8000
	s_addc_u32 s49, s19, 0
	v_cvt_pk_bf16_f32 v182, v182, v183
	v_cvt_pk_bf16_f32 v183, v184, v185
	v_cvt_pk_bf16_f32 v184, v186, v187
	v_cvt_pk_bf16_f32 v185, v188, v189
	v_cvt_pk_bf16_f32 v190, v190, v191
	v_cvt_pk_bf16_f32 v191, v192, v193
	v_cvt_pk_bf16_f32 v192, v194, v195
	v_cvt_pk_bf16_f32 v193, v196, v197
	v_add_f32_e32 v218, v166, v167
	s_nop 0
	v_permlane16_swap_b32_e32 v182, v184
	v_permlane16_swap_b32_e32 v183, v185
	v_permlane16_swap_b32_e32 v190, v192
	v_permlane16_swap_b32_e32 v191, v193
	global_store_dwordx4 v131, v[182:185], s[48:49]
	global_store_dwordx4 v131, v[190:193], s[48:49] offset:256
	v_mov_b32_e32 v219, v218
	s_nop 1
	v_permlane16_swap_b32_e32 v219, v218
	v_add_f32_e32 v218, v218, v219
	v_mov_b32_e32 v219, v218
	s_nop 1
	v_permlane32_swap_b32_e32 v219, v218
	v_add_f32_e32 v218, v218, v219
	s_and_saveexec_b64 s[0:1], s[40:41]
	global_atomic_add_f32 v130, v218, s[58:59] offset:64
	s_mov_b64 exec, s[0:1]
	v_pk_mul_f32 v[166:167], v[198:199], v[198:199]
	v_pk_mul_f32 v[144:145], v[200:201], v[200:201]
	v_pk_fma_f32 v[166:167], v[202:203], v[202:203], v[166:167]
	v_pk_fma_f32 v[144:145], v[204:205], v[204:205], v[144:145]
	v_pk_fma_f32 v[166:167], v[206:207], v[206:207], v[166:167]
	v_pk_fma_f32 v[144:145], v[208:209], v[208:209], v[144:145]
	v_pk_fma_f32 v[166:167], v[210:211], v[210:211], v[166:167]
	v_pk_fma_f32 v[144:145], v[212:213], v[212:213], v[144:145]
	s_nop 0
	v_pk_add_f32 v[166:167], v[166:167], v[144:145]
	s_add_u32 s48, s18, 0x10000
	s_addc_u32 s49, s19, 0
	v_cvt_pk_bf16_f32 v198, v198, v199
	v_cvt_pk_bf16_f32 v199, v200, v201
	v_cvt_pk_bf16_f32 v200, v202, v203
	v_cvt_pk_bf16_f32 v201, v204, v205
	v_cvt_pk_bf16_f32 v206, v206, v207
	v_cvt_pk_bf16_f32 v207, v208, v209
	v_cvt_pk_bf16_f32 v208, v210, v211
	v_cvt_pk_bf16_f32 v209, v212, v213
	v_add_f32_e32 v218, v166, v167
	s_nop 0
	v_permlane16_swap_b32_e32 v198, v200
	v_permlane16_swap_b32_e32 v199, v201
	v_permlane16_swap_b32_e32 v206, v208
	v_permlane16_swap_b32_e32 v207, v209
	global_store_dwordx4 v131, v[198:201], s[48:49]
	global_store_dwordx4 v131, v[206:209], s[48:49] offset:256
	v_mov_b32_e32 v219, v218
	s_nop 1
	v_permlane16_swap_b32_e32 v219, v218
	v_add_f32_e32 v218, v218, v219
	v_mov_b32_e32 v219, v218
	s_nop 1
	v_permlane32_swap_b32_e32 v219, v218
	v_add_f32_e32 v218, v218, v219
	s_and_saveexec_b64 s[0:1], s[40:41]
	global_atomic_add_f32 v130, v218, s[58:59] offset:128
	s_mov_b64 exec, s[0:1]
	v_pk_mul_f32 v[166:167], v[162:163], v[162:163]
	v_pk_mul_f32 v[144:145], v[164:165], v[164:165]
	v_pk_fma_f32 v[166:167], v[214:215], v[214:215], v[166:167]
	v_pk_fma_f32 v[144:145], v[216:217], v[216:217], v[144:145]
	v_pk_fma_f32 v[166:167], v[136:137], v[136:137], v[166:167]
	v_pk_fma_f32 v[144:145], v[138:139], v[138:139], v[144:145]
	v_pk_fma_f32 v[166:167], v[140:141], v[140:141], v[166:167]
	v_pk_fma_f32 v[144:145], v[142:143], v[142:143], v[144:145]
	s_nop 0
	v_pk_add_f32 v[166:167], v[166:167], v[144:145]
	s_add_u32 s48, s18, 0x18000
	s_addc_u32 s49, s19, 0
	v_cvt_pk_bf16_f32 v162, v162, v163
	v_cvt_pk_bf16_f32 v163, v164, v165
	v_cvt_pk_bf16_f32 v164, v214, v215
	v_cvt_pk_bf16_f32 v165, v216, v217
	v_cvt_pk_bf16_f32 v136, v136, v137
	v_cvt_pk_bf16_f32 v137, v138, v139
	v_cvt_pk_bf16_f32 v138, v140, v141
	v_cvt_pk_bf16_f32 v139, v142, v143
	v_add_f32_e32 v218, v166, v167
	s_nop 0
	v_permlane16_swap_b32_e32 v162, v164
	v_permlane16_swap_b32_e32 v163, v165
	v_permlane16_swap_b32_e32 v136, v138
	v_permlane16_swap_b32_e32 v137, v139
	global_store_dwordx4 v131, v[162:165], s[48:49]
	global_store_dwordx4 v131, v[136:139], s[48:49] offset:256
	v_mov_b32_e32 v219, v218
	s_nop 1
	v_permlane16_swap_b32_e32 v219, v218
	v_add_f32_e32 v218, v218, v219
	v_mov_b32_e32 v219, v218
	s_nop 1
	v_permlane32_swap_b32_e32 v219, v218
	v_add_f32_e32 v218, v218, v219
	s_and_saveexec_b64 s[0:1], s[40:41]
	global_atomic_add_f32 v130, v218, s[58:59] offset:192
	s_mov_b64 exec, s[0:1]
	s_waitcnt vmcnt(24)
	v_pk_add_f32 v[124:125], v[60:61], v[124:125]
	v_pk_add_f32 v[126:127], v[62:63], v[126:127]
	v_pk_add_f32 v[120:121], v[56:57], v[120:121]
	v_pk_add_f32 v[122:123], v[58:59], v[122:123]
	v_pk_add_f32 v[116:117], v[52:53], v[116:117]
	v_pk_add_f32 v[118:119], v[54:55], v[118:119]
	v_pk_add_f32 v[112:113], v[48:49], v[112:113]
	v_pk_add_f32 v[114:115], v[50:51], v[114:115]
	v_pk_mul_f32 v[166:167], v[124:125], v[124:125]
	v_pk_mul_f32 v[144:145], v[126:127], v[126:127]
	v_pk_fma_f32 v[166:167], v[120:121], v[120:121], v[166:167]
	v_pk_fma_f32 v[144:145], v[122:123], v[122:123], v[144:145]
	v_pk_fma_f32 v[166:167], v[116:117], v[116:117], v[166:167]
	v_pk_fma_f32 v[144:145], v[118:119], v[118:119], v[144:145]
	v_pk_fma_f32 v[166:167], v[112:113], v[112:113], v[166:167]
	v_pk_fma_f32 v[144:145], v[114:115], v[114:115], v[144:145]
	s_nop 0
	v_pk_add_f32 v[166:167], v[166:167], v[144:145]
	s_add_u32 s48, s18, 0x40000
	s_addc_u32 s49, s19, 0
	v_cvt_pk_bf16_f32 v124, v124, v125
	v_cvt_pk_bf16_f32 v125, v126, v127
	v_cvt_pk_bf16_f32 v126, v120, v121
	v_cvt_pk_bf16_f32 v127, v122, v123
	v_cvt_pk_bf16_f32 v116, v116, v117
	v_cvt_pk_bf16_f32 v117, v118, v119
	v_cvt_pk_bf16_f32 v118, v112, v113
	v_cvt_pk_bf16_f32 v119, v114, v115
	v_add_f32_e32 v218, v166, v167
	s_nop 0
	v_permlane16_swap_b32_e32 v124, v126
	v_permlane16_swap_b32_e32 v125, v127
	v_permlane16_swap_b32_e32 v116, v118
	v_permlane16_swap_b32_e32 v117, v119
	global_store_dwordx4 v131, v[124:127], s[48:49]
	global_store_dwordx4 v131, v[116:119], s[48:49] offset:256
	v_mov_b32_e32 v219, v218
	s_nop 1
	v_permlane16_swap_b32_e32 v219, v218
	v_add_f32_e32 v218, v218, v219
	v_mov_b32_e32 v219, v218
	s_nop 1
	v_permlane32_swap_b32_e32 v219, v218
	v_add_f32_e32 v218, v218, v219
	s_and_saveexec_b64 s[0:1], s[40:41]
	global_atomic_add_f32 v130, v218, s[58:59] offset:512
	s_mov_b64 exec, s[0:1]
	s_waitcnt vmcnt(23)
; DI u32x2 pk4(f32x4 v) { u32x2 r; r.x = pk2(v[0], v[1]); r.y = pk2(v[2], v[3]); return r; }
;     DI void operator()(const AccT& acc, const Unit& u, int wr, int wc, int fr, int fq, LAS unsigned char*) const {
;     ...
;                 const int row = u.pm * 256 + ai * 128 + wr * 64 + m * 16 + fr;
;                 const float* xr = (row < SEQ ? xp + (size_t)row * DM : xs + (size_t)(row - SEQ) * DM) + col0;
;                 bf16_t* brow = X1B + (size_t)(row < SEQ ? row + 2 : row + (X1B_PROMPT_ROWS - SEQ)) * DM + col0;
;                 float ss = 0.f;
; #pragma unroll
;                 for (int bj = 0; bj < 2; ++bj)
; #pragma unroll
;                     for (int n = 0; n < 2; ++n) {
;                         const int c = bj * 128 + n * 16;
;                         const f32x4 o = *(const f32x4*)(xr + c) + acc[ai][bj][m][n];
;                         *(u32x2*)(brow + c) = pk4(o);
;                         ss += (o[0] * o[0] + o[1] * o[1]) + (o[2] * o[2] + o[3] * o[3]);
;                     }
;                 ss += __shfl_xor(ss, 16); ss += __shfl_xor(ss, 32);
;                 if (fq == 0) unsafeAtomicAdd(sumsq + row, ss);
;             }
	v_pk_add_f32 v[108:109], v[44:45], v[108:109]
	v_pk_add_f32 v[110:111], v[46:47], v[110:111]
	v_pk_add_f32 v[104:105], v[40:41], v[104:105]
	v_pk_add_f32 v[106:107], v[42:43], v[106:107]
	v_pk_add_f32 v[100:101], v[36:37], v[100:101]
	v_pk_add_f32 v[102:103], v[38:39], v[102:103]
	v_pk_add_f32 v[96:97], v[32:33], v[96:97]
	v_pk_add_f32 v[98:99], v[34:35], v[98:99]
	v_pk_mul_f32 v[166:167], v[108:109], v[108:109]
	v_pk_mul_f32 v[144:145], v[110:111], v[110:111]
	v_pk_fma_f32 v[166:167], v[104:105], v[104:105], v[166:167]
	v_pk_fma_f32 v[144:145], v[106:107], v[106:107], v[144:145]
	v_pk_fma_f32 v[166:167], v[100:101], v[100:101], v[166:167]
	v_pk_fma_f32 v[144:145], v[102:103], v[102:103], v[144:145]
	v_pk_fma_f32 v[166:167], v[96:97], v[96:97], v[166:167]
	v_pk_fma_f32 v[144:145], v[98:99], v[98:99], v[144:145]
	s_nop 0
	v_pk_add_f32 v[166:167], v[166:167], v[144:145]
	s_add_u32 s48, s18, 0x48000
	s_addc_u32 s49, s19, 0
	v_cvt_pk_bf16_f32 v108, v108, v109
	v_cvt_pk_bf16_f32 v109, v110, v111
	v_cvt_pk_bf16_f32 v110, v104, v105
	v_cvt_pk_bf16_f32 v111, v106, v107
	v_cvt_pk_bf16_f32 v100, v100, v101
	v_cvt_pk_bf16_f32 v101, v102, v103
	v_cvt_pk_bf16_f32 v102, v96, v97
	v_cvt_pk_bf16_f32 v103, v98, v99
	v_add_f32_e32 v218, v166, v167
	s_nop 0
	v_permlane16_swap_b32_e32 v108, v110
	v_permlane16_swap_b32_e32 v109, v111
	v_permlane16_swap_b32_e32 v100, v102
	v_permlane16_swap_b32_e32 v101, v103
	global_store_dwordx4 v131, v[108:111], s[48:49]
	global_store_dwordx4 v131, v[100:103], s[48:49] offset:256
	v_mov_b32_e32 v219, v218
	s_nop 1
	v_permlane16_swap_b32_e32 v219, v218
	v_add_f32_e32 v218, v218, v219
	v_mov_b32_e32 v219, v218
	s_nop 1
	v_permlane32_swap_b32_e32 v219, v218
	v_add_f32_e32 v218, v218, v219
	s_and_saveexec_b64 s[0:1], s[40:41]
	global_atomic_add_f32 v130, v218, s[58:59] offset:576
	s_mov_b64 exec, s[0:1]
	s_waitcnt vmcnt(22)
	v_pk_add_f32 v[92:93], v[28:29], v[92:93]
	v_pk_add_f32 v[94:95], v[30:31], v[94:95]
	v_pk_add_f32 v[88:89], v[24:25], v[88:89]
	v_pk_add_f32 v[90:91], v[26:27], v[90:91]
	v_pk_add_f32 v[84:85], v[20:21], v[84:85]
	v_pk_add_f32 v[86:87], v[22:23], v[86:87]
	v_pk_add_f32 v[80:81], v[16:17], v[80:81]
	v_pk_add_f32 v[82:83], v[18:19], v[82:83]
	v_pk_mul_f32 v[166:167], v[92:93], v[92:93]
	v_pk_mul_f32 v[144:145], v[94:95], v[94:95]
	v_pk_fma_f32 v[166:167], v[88:89], v[88:89], v[166:167]
	v_pk_fma_f32 v[144:145], v[90:91], v[90:91], v[144:145]
	v_pk_fma_f32 v[166:167], v[84:85], v[84:85], v[166:167]
	v_pk_fma_f32 v[144:145], v[86:87], v[86:87], v[144:145]
	v_pk_fma_f32 v[166:167], v[80:81], v[80:81], v[166:167]
	v_pk_fma_f32 v[144:145], v[82:83], v[82:83], v[144:145]
	s_nop 0
	v_pk_add_f32 v[166:167], v[166:167], v[144:145]
	s_add_u32 s48, s18, 0x50000
	s_addc_u32 s49, s19, 0
	v_cvt_pk_bf16_f32 v92, v92, v93
	v_cvt_pk_bf16_f32 v93, v94, v95
	v_cvt_pk_bf16_f32 v94, v88, v89
	v_cvt_pk_bf16_f32 v95, v90, v91
	v_cvt_pk_bf16_f32 v84, v84, v85
	v_cvt_pk_bf16_f32 v85, v86, v87
	v_cvt_pk_bf16_f32 v86, v80, v81
	v_cvt_pk_bf16_f32 v87, v82, v83
	v_add_f32_e32 v218, v166, v167
	s_nop 0
	v_permlane16_swap_b32_e32 v92, v94
	v_permlane16_swap_b32_e32 v93, v95
	v_permlane16_swap_b32_e32 v84, v86
	v_permlane16_swap_b32_e32 v85, v87
	global_store_dwordx4 v131, v[92:95], s[48:49]
	global_store_dwordx4 v131, v[84:87], s[48:49] offset:256
	v_mov_b32_e32 v219, v218
	s_nop 1
	v_permlane16_swap_b32_e32 v219, v218
	v_add_f32_e32 v218, v218, v219
	v_mov_b32_e32 v219, v218
	s_nop 1
	v_permlane32_swap_b32_e32 v219, v218
	v_add_f32_e32 v218, v218, v219
	s_and_saveexec_b64 s[0:1], s[40:41]
	global_atomic_add_f32 v130, v218, s[58:59] offset:640
	s_mov_b64 exec, s[0:1]
	s_waitcnt vmcnt(21)
	v_pk_add_f32 v[76:77], v[12:13], v[76:77]
	v_pk_add_f32 v[78:79], v[14:15], v[78:79]
	v_pk_add_f32 v[72:73], v[8:9], v[72:73]
	v_pk_add_f32 v[74:75], v[10:11], v[74:75]
	v_pk_add_f32 v[68:69], v[4:5], v[68:69]
	v_pk_add_f32 v[70:71], v[6:7], v[70:71]
	v_pk_add_f32 v[64:65], v[0:1], v[64:65]
	v_pk_add_f32 v[66:67], v[2:3], v[66:67]
	v_pk_mul_f32 v[166:167], v[76:77], v[76:77]
	v_pk_mul_f32 v[144:145], v[78:79], v[78:79]
	v_pk_fma_f32 v[166:167], v[72:73], v[72:73], v[166:167]
	v_pk_fma_f32 v[144:145], v[74:75], v[74:75], v[144:145]
	v_pk_fma_f32 v[166:167], v[68:69], v[68:69], v[166:167]
	v_pk_fma_f32 v[144:145], v[70:71], v[70:71], v[144:145]
	v_pk_fma_f32 v[166:167], v[64:65], v[64:65], v[166:167]
	v_pk_fma_f32 v[144:145], v[66:67], v[66:67], v[144:145]
	s_nop 0
	v_pk_add_f32 v[166:167], v[166:167], v[144:145]
	s_add_u32 s48, s18, 0x58000
	s_addc_u32 s49, s19, 0
	v_cvt_pk_bf16_f32 v76, v76, v77
	v_cvt_pk_bf16_f32 v77, v78, v79
	v_cvt_pk_bf16_f32 v78, v72, v73
	v_cvt_pk_bf16_f32 v79, v74, v75
	v_cvt_pk_bf16_f32 v68, v68, v69
	v_cvt_pk_bf16_f32 v69, v70, v71
	v_cvt_pk_bf16_f32 v70, v64, v65
	v_cvt_pk_bf16_f32 v71, v66, v67
	v_add_f32_e32 v218, v166, v167
	s_nop 0
	v_permlane16_swap_b32_e32 v76, v78
	v_permlane16_swap_b32_e32 v77, v79
	v_permlane16_swap_b32_e32 v68, v70
	v_permlane16_swap_b32_e32 v69, v71
	global_store_dwordx4 v131, v[76:79], s[48:49]
	global_store_dwordx4 v131, v[68:71], s[48:49] offset:256
	v_mov_b32_e32 v219, v218
	s_nop 1
	v_permlane16_swap_b32_e32 v219, v218
	v_add_f32_e32 v218, v218, v219
	v_mov_b32_e32 v219, v218
	s_nop 1
	v_permlane32_swap_b32_e32 v219, v218
	v_add_f32_e32 v218, v218, v219
	s_and_saveexec_b64 s[0:1], s[40:41]
	global_atomic_add_f32 v130, v218, s[58:59] offset:704
	s_mov_b64 exec, s[0:1]
	s_cmp_eq_u32 s30, s28
	s_mov_b64 s[0:1], -1
	s_cbranch_scc1 .LBB0_955
